# live fp4 conversion stream loops (ph6/ph8): per-row amax/sum all-reduce on permlane swaps + DPP instead of six ds_bpermute rounds
# baseline (speedup 1.0000x reference)
.LBB0_1751:
	s_andn2_saveexec_b64 s[16:17], s[2:3]
	s_cbranch_execz .LBB0_1744
	v_add_u32_e32 v9, 0xffffc000, v8
	v_cmp_lt_i32_e64 s[2:3], s23, v8
	v_mov_b32_e32 v19, s89
	v_xor_b32_e32 v54, 8, v13
	v_cndmask_b32_e64 v8, v8, v9, s[2:3]
	v_mov_b32_e32 v9, s59
	v_cndmask_b32_e64 v21, v9, v19, s[2:3]
	v_mov_b32_e32 v9, s58
	v_mov_b32_e32 v19, s88
	v_cndmask_b32_e64 v20, v9, v19, s[2:3]
	v_ashrrev_i32_e32 v9, 31, v8
	v_lshlrev_b64 v[22:23], 13, v[8:9]
	v_lshl_add_u64 v[20:21], v[20:21], 0, v[22:23]
	v_lshl_add_u64 v[36:37], v[20:21], 0, v[2:3]
	v_add_co_u32_e32 v52, vcc, s22, v36
	global_load_dwordx4 v[20:23], v[36:37], off nt
	global_load_dwordx4 v[24:27], v[36:37], off offset:1024 nt
	global_load_dwordx4 v[28:31], v[36:37], off offset:2048 nt
	global_load_dwordx4 v[32:35], v[36:37], off offset:3072 nt
	v_addc_co_u32_e32 v53, vcc, 0, v37, vcc
	global_load_dwordx4 v[36:39], v[52:53], off nt
	global_load_dwordx4 v[40:43], v[52:53], off offset:1024 nt
	global_load_dwordx4 v[44:47], v[52:53], off offset:2048 nt
	global_load_dwordx4 v[48:51], v[52:53], off offset:3072 nt
	v_and_b32_e32 v19, 64, v13
	v_xor_b32_e32 v52, 32, v13
	v_add_u32_e32 v19, 64, v19
	v_cmp_lt_i32_e32 vcc, v52, v19
	v_xor_b32_e32 v53, 16, v13
	v_xor_b32_e32 v55, 4, v13
	v_cndmask_b32_e32 v52, v13, v52, vcc
	v_lshlrev_b32_e32 v52, 2, v52
	v_cmp_lt_i32_e32 vcc, v53, v19
	v_xor_b32_e32 v56, 2, v13
	v_xor_b32_e32 v57, 1, v13
	v_cndmask_b32_e32 v53, v13, v53, vcc
	v_lshlrev_b32_e32 v53, 2, v53
	v_cmp_lt_i32_e32 vcc, v54, v19
	s_waitcnt vmcnt(7)
	ds_write_b128 v10, v[20:23]
	s_waitcnt vmcnt(6)
	ds_write_b128 v10, v[24:27] offset:1024
	s_waitcnt vmcnt(5)
	ds_write_b128 v10, v[28:31] offset:2048
	s_waitcnt vmcnt(4)
	ds_write_b128 v10, v[32:35] offset:3072
	s_waitcnt vmcnt(3)
	ds_write_b128 v10, v[36:39] offset:4096
	s_waitcnt vmcnt(2)
	ds_write_b128 v10, v[40:43] offset:5120
	s_waitcnt vmcnt(1)
	ds_write_b128 v10, v[44:47] offset:6144
	s_waitcnt vmcnt(0)
	ds_write_b128 v10, v[48:51] offset:7168
	s_waitcnt lgkmcnt(0)
	ds_read_b128 v[20:23], v11
	ds_read_b128 v[24:27], v11 offset:16
	ds_read_b128 v[28:31], v11 offset:32
	ds_read_b128 v[32:35], v11 offset:48
	ds_read_b128 v[36:39], v11 offset:64
	ds_read_b128 v[40:43], v11 offset:80
	ds_read_b128 v[44:47], v11 offset:96
	ds_read_b128 v[48:51], v11 offset:112
	s_waitcnt lgkmcnt(7)
	v_mul_f32_e32 v59, v21, v21
	v_fmac_f32_e32 v59, v20, v20
	v_fmac_f32_e32 v59, v22, v22
	v_fmac_f32_e32 v59, v23, v23
	s_waitcnt lgkmcnt(6)
	v_fmac_f32_e32 v59, v24, v24
	v_fmac_f32_e32 v59, v25, v25
	v_fmac_f32_e32 v59, v26, v26
	v_fmac_f32_e32 v59, v27, v27
	s_waitcnt lgkmcnt(5)
	v_fmac_f32_e32 v59, v28, v28
	v_fmac_f32_e32 v59, v29, v29
	v_fmac_f32_e32 v59, v30, v30
	v_fmac_f32_e32 v59, v31, v31
	s_waitcnt lgkmcnt(4)
	v_fmac_f32_e32 v59, v32, v32
	v_fmac_f32_e32 v59, v33, v33
	v_fmac_f32_e32 v59, v34, v34
	v_max3_f32 v58, |v20|, 0, |v21|
	v_fmac_f32_e32 v59, v35, v35
	v_max3_f32 v58, v58, |v22|, |v23|
	s_waitcnt lgkmcnt(3)
	v_fmac_f32_e32 v59, v36, v36
	v_max3_f32 v58, v58, |v24|, |v25|
	v_fmac_f32_e32 v59, v37, v37
	v_max3_f32 v58, v58, |v26|, |v27|
	v_fmac_f32_e32 v59, v38, v38
	v_max3_f32 v58, v58, |v28|, |v29|
	v_fmac_f32_e32 v59, v39, v39
	v_max3_f32 v58, v58, |v30|, |v31|
	s_waitcnt lgkmcnt(2)
	v_fmac_f32_e32 v59, v40, v40
	v_max3_f32 v58, v58, |v32|, |v33|
	v_fmac_f32_e32 v59, v41, v41
	v_max3_f32 v58, v58, |v34|, |v35|
	v_fmac_f32_e32 v59, v42, v42
	v_max3_f32 v58, v58, |v36|, |v37|
	v_fmac_f32_e32 v59, v43, v43
	v_max3_f32 v58, v58, |v38|, |v39|
	s_waitcnt lgkmcnt(1)
	v_fmac_f32_e32 v59, v44, v44
	v_max3_f32 v58, v58, |v40|, |v41|
	v_fmac_f32_e32 v59, v45, v45
	v_max3_f32 v58, v58, |v42|, |v43|
	v_fmac_f32_e32 v59, v46, v46
	v_max3_f32 v58, v58, |v44|, |v45|
	v_fmac_f32_e32 v59, v47, v47
	v_max3_f32 v58, v58, |v46|, |v47|
	s_waitcnt lgkmcnt(0)
	v_fmac_f32_e32 v59, v48, v48
	v_max3_f32 v58, v58, |v48|, |v49|
	v_fmac_f32_e32 v59, v49, v49
	v_max3_f32 v58, v58, |v50|, |v51|
	v_fmac_f32_e32 v59, v50, v50
	v_fmac_f32_e32 v59, v51, v51
	v_mov_b32_e32 v60, v58
	v_mov_b32_e32 v53, v59
	s_nop 1
	v_permlane32_swap_b32_e32 v60, v58
	v_permlane32_swap_b32_e32 v53, v59
	v_max_f32_e32 v58, v58, v60
	v_add_f32_e32 v59, v59, v53
	v_mov_b32_e32 v60, v58
	v_mov_b32_e32 v53, v59
	s_nop 1
	v_permlane16_swap_b32_e32 v60, v58
	v_permlane16_swap_b32_e32 v53, v59
	v_max_f32_e32 v58, v58, v60
	v_add_f32_e32 v59, v59, v53
	s_nop 0
	v_max_f32_dpp v58, v58, v58 row_ror:8 row_mask:0xf bank_mask:0xf
	v_add_f32_dpp v59, v59, v59 row_ror:8 row_mask:0xf bank_mask:0xf
	s_nop 0
	v_max_f32_dpp v58, v58, v58 row_ror:4 row_mask:0xf bank_mask:0xf
	v_add_f32_dpp v59, v59, v59 row_ror:4 row_mask:0xf bank_mask:0xf
	s_nop 0
	v_max_f32_dpp v58, v58, v58 row_ror:2 row_mask:0xf bank_mask:0xf
	v_add_f32_dpp v59, v59, v59 row_ror:2 row_mask:0xf bank_mask:0xf
	s_nop 0
	v_max_f32_dpp v58, v58, v58 row_ror:1 row_mask:0xf bank_mask:0xf
	v_add_f32_dpp v59, v59, v59 row_ror:1 row_mask:0xf bank_mask:0xf
	v_mul_f32_e32 v52, 0x3a000000, v59
	v_mul_f32_e32 v53, 0x4f800000, v52
	v_cmp_gt_f32_e32 vcc, s24, v52
	v_mov_b32_e32 v19, v58
	s_nop 0
	v_cndmask_b32_e32 v52, v52, v53, vcc
	v_sqrt_f32_e32 v53, v52
	v_mul_f32_e32 v19, 0x3e000000, v19
	v_add_u32_e32 v54, -1, v53
	v_add_u32_e32 v55, 1, v53
	v_fma_f32 v56, -v54, v53, v52
	v_fma_f32 v57, -v55, v53, v52
	v_cmp_ge_f32_e64 s[4:5], 0, v56
	s_nop 1
	v_cndmask_b32_e64 v53, v53, v54, s[4:5]
	v_cmp_lt_f32_e64 s[4:5], 0, v57
	s_nop 1
	v_cndmask_b32_e64 v53, v53, v55, s[4:5]
	v_mul_f32_e32 v54, 0x37800000, v53
	v_cndmask_b32_e32 v53, v53, v54, vcc
	v_cmp_class_f32_e32 vcc, v52, v12
	s_nop 1
	v_cndmask_b32_e32 v52, v53, v52, vcc
	v_mul_f32_e32 v52, 0.5, v52
	v_max3_f32 v19, v52, v19, s25
	v_div_scale_f32 v52, s[4:5], v19, v19, 1.0
	v_rcp_f32_e32 v53, v52
	v_div_scale_f32 v54, vcc, 1.0, v19, 1.0
	v_fma_f32 v55, -v52, v53, 1.0
	v_fmac_f32_e32 v53, v55, v53
	v_mul_f32_e32 v55, v54, v53
	v_fma_f32 v56, -v52, v55, v54
	v_fmac_f32_e32 v55, v56, v53
	v_fma_f32 v52, -v52, v55, v54
	v_div_fmas_f32 v52, v52, v53, v55
	v_div_fixup_f32 v52, v52, v19, 1.0
	v_mul_f32_e32 v20, v20, v52
	v_med3_f32 v53, v20, s26, v14
	v_mul_f32_e32 v20, v26, v52
	v_med3_f32 v26, v20, s26, v14
	v_mul_f32_e32 v20, v27, v52
	v_med3_f32 v27, v20, s26, v14
	v_mul_f32_e32 v20, v28, v52
	v_med3_f32 v28, v20, s26, v14
	v_mul_f32_e32 v20, v29, v52
	v_med3_f32 v29, v20, s26, v14
	v_mul_f32_e32 v20, v30, v52
	v_med3_f32 v30, v20, s26, v14
	v_mul_f32_e32 v20, v31, v52
	v_med3_f32 v31, v20, s26, v14
	v_mul_f32_e32 v20, v32, v52
	v_med3_f32 v32, v20, s26, v14
	v_mul_f32_e32 v20, v33, v52
	v_med3_f32 v33, v20, s26, v14
	v_mul_f32_e32 v20, v34, v52
	v_med3_f32 v34, v20, s26, v14
	v_mul_f32_e32 v20, v35, v52
	v_med3_f32 v35, v20, s26, v14
	v_mul_f32_e32 v20, v36, v52
	v_med3_f32 v36, v20, s26, v14
	v_mul_f32_e32 v20, v37, v52
	v_med3_f32 v37, v20, s26, v14
	v_mul_f32_e32 v20, v38, v52
	v_med3_f32 v38, v20, s26, v14
	v_mul_f32_e32 v20, v39, v52
	v_med3_f32 v39, v20, s26, v14
	v_mul_f32_e32 v20, v40, v52
	v_med3_f32 v40, v20, s26, v14
	v_mul_f32_e32 v20, v41, v52
	v_med3_f32 v41, v20, s26, v14
	v_mul_f32_e32 v20, v42, v52
	v_med3_f32 v42, v20, s26, v14
	v_mul_f32_e32 v20, v43, v52
	v_med3_f32 v43, v20, s26, v14
	v_mul_f32_e32 v20, v44, v52
	v_med3_f32 v44, v20, s26, v14
	v_mul_f32_e32 v20, v45, v52
	v_med3_f32 v45, v20, s26, v14
	v_mul_f32_e32 v20, v46, v52
	v_med3_f32 v46, v20, s26, v14
	v_mul_f32_e32 v20, v47, v52
	v_med3_f32 v47, v20, s26, v14
	v_mul_f32_e32 v20, v48, v52
	v_med3_f32 v48, v20, s26, v14
	v_mul_f32_e32 v20, v49, v52
	v_med3_f32 v49, v20, s26, v14
	v_mul_f32_e32 v20, v50, v52
	v_mul_f32_e32 v21, v21, v52
	v_med3_f32 v50, v20, s26, v14
	v_mul_f32_e32 v20, v51, v52
	v_mul_f32_e32 v22, v22, v52
	v_mul_f32_e32 v23, v23, v52
	v_med3_f32 v21, v21, s26, v14
	v_med3_f32 v51, v20, s26, v14
	v_mov_b32_e32 v20, v3
	v_mul_f32_e32 v24, v24, v52
	v_mul_f32_e32 v25, v25, v52
	v_med3_f32 v22, v22, s26, v14
	v_med3_f32 v23, v23, s26, v14
	v_cvt_scalef32_pk_fp4_f32 v20, v53, v21, 1.0
	v_med3_f32 v24, v24, s26, v14
	v_med3_f32 v25, v25, s26, v14
	v_cvt_scalef32_pk_fp4_f32 v20, v22, v23, 1.0 op_sel:[0,0,1,0]
	v_mov_b32_e32 v21, v3
	v_mov_b32_e32 v22, v3
	v_mov_b32_e32 v23, v3
	v_cvt_scalef32_pk_fp4_f32 v20, v24, v25, 1.0 op_sel:[0,0,0,1]
	v_cvt_scalef32_pk_fp4_f32 v21, v28, v29, 1.0
	v_cvt_scalef32_pk_fp4_f32 v22, v36, v37, 1.0
	v_cvt_scalef32_pk_fp4_f32 v23, v44, v45, 1.0
	v_cndmask_b32_e64 v24, v15, v16, s[2:3]
	v_mov_b32_e32 v25, v3
	v_cvt_scalef32_pk_fp4_f32 v20, v26, v27, 1.0 op_sel:[0,0,1,1]
	v_cvt_scalef32_pk_fp4_f32 v21, v30, v31, 1.0 op_sel:[0,0,1,0]
	v_cvt_scalef32_pk_fp4_f32 v22, v38, v39, 1.0 op_sel:[0,0,1,0]
	v_cvt_scalef32_pk_fp4_f32 v23, v46, v47, 1.0 op_sel:[0,0,1,0]
	v_lshl_add_u64 v[24:25], s[92:93], 0, v[24:25]
	v_lshlrev_b64 v[26:27], 10, v[8:9]
	v_cvt_scalef32_pk_fp4_f32 v21, v32, v33, 1.0 op_sel:[0,0,0,1]
	v_cvt_scalef32_pk_fp4_f32 v22, v40, v41, 1.0 op_sel:[0,0,0,1]
	v_cvt_scalef32_pk_fp4_f32 v23, v48, v49, 1.0 op_sel:[0,0,0,1]
	v_lshl_add_u64 v[24:25], v[24:25], 0, v[26:27]
	v_cvt_scalef32_pk_fp4_f32 v21, v34, v35, 1.0 op_sel:[0,0,1,1]
	v_cvt_scalef32_pk_fp4_f32 v22, v42, v43, 1.0 op_sel:[0,0,1,1]
	v_cvt_scalef32_pk_fp4_f32 v23, v50, v51, 1.0 op_sel:[0,0,1,1]
	v_lshl_add_u64 v[24:25], v[24:25], 0, v[6:7]
	global_store_dwordx4 v[24:25], v[20:23], off
	s_and_saveexec_b64 s[4:5], s[0:1]
	s_cbranch_execz .LBB0_1743
	v_cndmask_b32_e64 v20, v17, v18, s[2:3]
	v_mov_b32_e32 v21, v3
	v_lshl_add_u64 v[20:21], s[92:93], 0, v[20:21]
	v_lshl_add_u64 v[8:9], v[8:9], 2, v[20:21]
	global_store_dword v[8:9], v19, off
	s_branch .LBB0_1743

.LBB0_1914:
	s_andn2_saveexec_b64 s[16:17], s[2:3]
	s_cbranch_execz .LBB0_1907
	v_add_u32_e32 v8, 0xffffc700, v8
	v_cmp_lt_i32_e64 s[2:3], s23, v9
	v_mov_b32_e32 v21, s89
	v_xor_b32_e32 v56, 8, v15
	v_cndmask_b32_e64 v8, v9, v8, s[2:3]
	v_mov_b32_e32 v9, s59
	v_cndmask_b32_e64 v23, v9, v21, s[2:3]
	v_mov_b32_e32 v9, s58
	v_mov_b32_e32 v21, s88
	v_cndmask_b32_e64 v22, v9, v21, s[2:3]
	v_ashrrev_i32_e32 v9, 31, v8
	v_lshlrev_b64 v[24:25], 13, v[8:9]
	v_lshl_add_u64 v[22:23], v[22:23], 0, v[24:25]
	v_lshl_add_u64 v[38:39], v[22:23], 0, v[2:3]
	v_add_co_u32_e32 v54, vcc, s22, v38
	global_load_dwordx4 v[22:25], v[38:39], off nt
	global_load_dwordx4 v[26:29], v[38:39], off offset:1024 nt
	global_load_dwordx4 v[30:33], v[38:39], off offset:2048 nt
	global_load_dwordx4 v[34:37], v[38:39], off offset:3072 nt
	v_addc_co_u32_e32 v55, vcc, 0, v39, vcc
	global_load_dwordx4 v[38:41], v[54:55], off nt
	global_load_dwordx4 v[42:45], v[54:55], off offset:1024 nt
	global_load_dwordx4 v[46:49], v[54:55], off offset:2048 nt
	global_load_dwordx4 v[50:53], v[54:55], off offset:3072 nt
	v_and_b32_e32 v21, 64, v15
	v_xor_b32_e32 v54, 32, v15
	v_add_u32_e32 v21, 64, v21
	v_cmp_lt_i32_e32 vcc, v54, v21
	v_xor_b32_e32 v55, 16, v15
	v_xor_b32_e32 v57, 4, v15
	v_cndmask_b32_e32 v54, v15, v54, vcc
	v_lshlrev_b32_e32 v54, 2, v54
	v_cmp_lt_i32_e32 vcc, v55, v21
	v_xor_b32_e32 v58, 2, v15
	v_xor_b32_e32 v59, 1, v15
	v_cndmask_b32_e32 v55, v15, v55, vcc
	v_lshlrev_b32_e32 v55, 2, v55
	v_cmp_lt_i32_e32 vcc, v56, v21
	s_waitcnt vmcnt(7)
	ds_write_b128 v1, v[22:25]
	s_waitcnt vmcnt(6)
	ds_write_b128 v1, v[26:29] offset:1024
	s_waitcnt vmcnt(5)
	ds_write_b128 v1, v[30:33] offset:2048
	s_waitcnt vmcnt(4)
	ds_write_b128 v1, v[34:37] offset:3072
	s_waitcnt vmcnt(3)
	ds_write_b128 v1, v[38:41] offset:4096
	s_waitcnt vmcnt(2)
	ds_write_b128 v1, v[42:45] offset:5120
	s_waitcnt vmcnt(1)
	ds_write_b128 v1, v[46:49] offset:6144
	s_waitcnt vmcnt(0)
	ds_write_b128 v1, v[50:53] offset:7168
	s_waitcnt lgkmcnt(0)
	ds_read_b128 v[22:25], v13
	ds_read_b128 v[26:29], v13 offset:16
	ds_read_b128 v[30:33], v13 offset:32
	ds_read_b128 v[34:37], v13 offset:48
	ds_read_b128 v[38:41], v13 offset:64
	ds_read_b128 v[42:45], v13 offset:80
	ds_read_b128 v[46:49], v13 offset:96
	ds_read_b128 v[50:53], v13 offset:112
	s_waitcnt lgkmcnt(7)
	v_mul_f32_e32 v61, v23, v23
	v_fmac_f32_e32 v61, v22, v22
	v_fmac_f32_e32 v61, v24, v24
	v_fmac_f32_e32 v61, v25, v25
	s_waitcnt lgkmcnt(6)
	v_fmac_f32_e32 v61, v26, v26
	v_fmac_f32_e32 v61, v27, v27
	v_fmac_f32_e32 v61, v28, v28
	v_fmac_f32_e32 v61, v29, v29
	s_waitcnt lgkmcnt(5)
	v_fmac_f32_e32 v61, v30, v30
	v_fmac_f32_e32 v61, v31, v31
	v_fmac_f32_e32 v61, v32, v32
	v_fmac_f32_e32 v61, v33, v33
	s_waitcnt lgkmcnt(4)
	v_fmac_f32_e32 v61, v34, v34
	v_fmac_f32_e32 v61, v35, v35
	v_fmac_f32_e32 v61, v36, v36
	v_max3_f32 v60, |v22|, 0, |v23|
	v_fmac_f32_e32 v61, v37, v37
	v_max3_f32 v60, v60, |v24|, |v25|
	s_waitcnt lgkmcnt(3)
	v_fmac_f32_e32 v61, v38, v38
	v_max3_f32 v60, v60, |v26|, |v27|
	v_fmac_f32_e32 v61, v39, v39
	v_max3_f32 v60, v60, |v28|, |v29|
	v_fmac_f32_e32 v61, v40, v40
	v_max3_f32 v60, v60, |v30|, |v31|
	v_fmac_f32_e32 v61, v41, v41
	v_max3_f32 v60, v60, |v32|, |v33|
	s_waitcnt lgkmcnt(2)
	v_fmac_f32_e32 v61, v42, v42
	v_max3_f32 v60, v60, |v34|, |v35|
	v_fmac_f32_e32 v61, v43, v43
	v_max3_f32 v60, v60, |v36|, |v37|
	v_fmac_f32_e32 v61, v44, v44
	v_max3_f32 v60, v60, |v38|, |v39|
	v_fmac_f32_e32 v61, v45, v45
	v_max3_f32 v60, v60, |v40|, |v41|
	s_waitcnt lgkmcnt(1)
	v_fmac_f32_e32 v61, v46, v46
	v_max3_f32 v60, v60, |v42|, |v43|
	v_fmac_f32_e32 v61, v47, v47
	v_max3_f32 v60, v60, |v44|, |v45|
	v_fmac_f32_e32 v61, v48, v48
	v_max3_f32 v60, v60, |v46|, |v47|
	v_fmac_f32_e32 v61, v49, v49
	v_max3_f32 v60, v60, |v48|, |v49|
	s_waitcnt lgkmcnt(0)
	v_fmac_f32_e32 v61, v50, v50
	v_max3_f32 v60, v60, |v50|, |v51|
	v_fmac_f32_e32 v61, v51, v51
	v_max3_f32 v60, v60, |v52|, |v53|
	v_fmac_f32_e32 v61, v52, v52
	v_fmac_f32_e32 v61, v53, v53
	v_mov_b32_e32 v54, v60
	v_mov_b32_e32 v55, v61
	s_nop 1
	v_permlane32_swap_b32_e32 v54, v60
	v_permlane32_swap_b32_e32 v55, v61
	v_max_f32_e32 v60, v60, v54
	v_add_f32_e32 v61, v61, v55
	v_mov_b32_e32 v54, v60
	v_mov_b32_e32 v55, v61
	s_nop 1
	v_permlane16_swap_b32_e32 v54, v60
	v_permlane16_swap_b32_e32 v55, v61
	v_max_f32_e32 v60, v60, v54
	v_add_f32_e32 v61, v61, v55
	s_nop 0
	v_max_f32_dpp v60, v60, v60 row_ror:8 row_mask:0xf bank_mask:0xf
	v_add_f32_dpp v61, v61, v61 row_ror:8 row_mask:0xf bank_mask:0xf
	s_nop 0
	v_max_f32_dpp v60, v60, v60 row_ror:4 row_mask:0xf bank_mask:0xf
	v_add_f32_dpp v61, v61, v61 row_ror:4 row_mask:0xf bank_mask:0xf
	s_nop 0
	v_max_f32_dpp v60, v60, v60 row_ror:2 row_mask:0xf bank_mask:0xf
	v_add_f32_dpp v61, v61, v61 row_ror:2 row_mask:0xf bank_mask:0xf
	s_nop 0
	v_max_f32_dpp v60, v60, v60 row_ror:1 row_mask:0xf bank_mask:0xf
	v_add_f32_dpp v61, v61, v61 row_ror:1 row_mask:0xf bank_mask:0xf
	v_mul_f32_e32 v54, 0x3a000000, v61
	v_mul_f32_e32 v55, 0x4f800000, v54
	v_cmp_gt_f32_e32 vcc, s24, v54
	v_mov_b32_e32 v21, v60
	s_nop 0
	v_cndmask_b32_e32 v54, v54, v55, vcc
	v_sqrt_f32_e32 v55, v54
	v_mul_f32_e32 v21, 0x3e000000, v21
	v_add_u32_e32 v56, -1, v55
	v_add_u32_e32 v57, 1, v55
	v_fma_f32 v58, -v56, v55, v54
	v_fma_f32 v59, -v57, v55, v54
	v_cmp_ge_f32_e64 s[4:5], 0, v58
	s_nop 1
	v_cndmask_b32_e64 v55, v55, v56, s[4:5]
	v_cmp_lt_f32_e64 s[4:5], 0, v59
	s_nop 1
	v_cndmask_b32_e64 v55, v55, v57, s[4:5]
	v_mul_f32_e32 v56, 0x37800000, v55
	v_cndmask_b32_e32 v55, v55, v56, vcc
	v_cmp_class_f32_e32 vcc, v54, v14
	s_nop 1
	v_cndmask_b32_e32 v54, v55, v54, vcc
	v_mul_f32_e32 v54, 0.5, v54
	v_max3_f32 v21, v54, v21, s25
	v_div_scale_f32 v54, s[4:5], v21, v21, 1.0
	v_rcp_f32_e32 v55, v54
	v_div_scale_f32 v56, vcc, 1.0, v21, 1.0
	v_fma_f32 v57, -v54, v55, 1.0
	v_fmac_f32_e32 v55, v57, v55
	v_mul_f32_e32 v57, v56, v55
	v_fma_f32 v58, -v54, v57, v56
	v_fmac_f32_e32 v57, v58, v55
	v_fma_f32 v54, -v54, v57, v56
	v_div_fmas_f32 v54, v54, v55, v57
	v_div_fixup_f32 v54, v54, v21, 1.0
	v_mul_f32_e32 v22, v22, v54
	v_med3_f32 v55, v22, s26, v16
	v_mul_f32_e32 v22, v28, v54
	v_med3_f32 v28, v22, s26, v16
	v_mul_f32_e32 v22, v29, v54
	v_med3_f32 v29, v22, s26, v16
	v_mul_f32_e32 v22, v30, v54
	v_med3_f32 v30, v22, s26, v16
	v_mul_f32_e32 v22, v31, v54
	v_med3_f32 v31, v22, s26, v16
	v_mul_f32_e32 v22, v32, v54
	v_med3_f32 v32, v22, s26, v16
	v_mul_f32_e32 v22, v33, v54
	v_med3_f32 v33, v22, s26, v16
	v_mul_f32_e32 v22, v34, v54
	v_med3_f32 v34, v22, s26, v16
	v_mul_f32_e32 v22, v35, v54
	v_med3_f32 v35, v22, s26, v16
	v_mul_f32_e32 v22, v36, v54
	v_med3_f32 v36, v22, s26, v16
	v_mul_f32_e32 v22, v37, v54
	v_med3_f32 v37, v22, s26, v16
	v_mul_f32_e32 v22, v38, v54
	v_med3_f32 v38, v22, s26, v16
	v_mul_f32_e32 v22, v39, v54
	v_med3_f32 v39, v22, s26, v16
	v_mul_f32_e32 v22, v40, v54
	v_med3_f32 v40, v22, s26, v16
	v_mul_f32_e32 v22, v41, v54
	v_med3_f32 v41, v22, s26, v16
	v_mul_f32_e32 v22, v42, v54
	v_med3_f32 v42, v22, s26, v16
	v_mul_f32_e32 v22, v43, v54
	v_med3_f32 v43, v22, s26, v16
	v_mul_f32_e32 v22, v44, v54
	v_med3_f32 v44, v22, s26, v16
	v_mul_f32_e32 v22, v45, v54
	v_med3_f32 v45, v22, s26, v16
	v_mul_f32_e32 v22, v46, v54
	v_med3_f32 v46, v22, s26, v16
	v_mul_f32_e32 v22, v47, v54
	v_med3_f32 v47, v22, s26, v16
	v_mul_f32_e32 v22, v48, v54
	v_med3_f32 v48, v22, s26, v16
	v_mul_f32_e32 v22, v49, v54
	v_med3_f32 v49, v22, s26, v16
	v_mul_f32_e32 v22, v50, v54
	v_med3_f32 v50, v22, s26, v16
	v_mul_f32_e32 v22, v51, v54
	v_med3_f32 v51, v22, s26, v16
	v_mul_f32_e32 v22, v52, v54
	v_mul_f32_e32 v23, v23, v54
	v_med3_f32 v52, v22, s26, v16
	v_mul_f32_e32 v22, v53, v54
	v_mul_f32_e32 v24, v24, v54
	v_mul_f32_e32 v25, v25, v54
	v_med3_f32 v23, v23, s26, v16
	v_med3_f32 v53, v22, s26, v16
	v_mov_b32_e32 v22, v3
	v_mul_f32_e32 v26, v26, v54
	v_mul_f32_e32 v27, v27, v54
	v_med3_f32 v24, v24, s26, v16
	v_med3_f32 v25, v25, s26, v16
	v_cvt_scalef32_pk_fp4_f32 v22, v55, v23, 1.0
	v_med3_f32 v26, v26, s26, v16
	v_med3_f32 v27, v27, s26, v16
	v_cvt_scalef32_pk_fp4_f32 v22, v24, v25, 1.0 op_sel:[0,0,1,0]
	v_mov_b32_e32 v23, v3
	v_mov_b32_e32 v24, v3
	v_mov_b32_e32 v25, v3
	v_cvt_scalef32_pk_fp4_f32 v22, v26, v27, 1.0 op_sel:[0,0,0,1]
	v_cvt_scalef32_pk_fp4_f32 v23, v30, v31, 1.0
	v_cvt_scalef32_pk_fp4_f32 v24, v38, v39, 1.0
	v_cvt_scalef32_pk_fp4_f32 v25, v46, v47, 1.0
	v_cndmask_b32_e64 v26, v17, v18, s[2:3]
	v_mov_b32_e32 v27, v3
	v_cvt_scalef32_pk_fp4_f32 v22, v28, v29, 1.0 op_sel:[0,0,1,1]
	v_cvt_scalef32_pk_fp4_f32 v23, v32, v33, 1.0 op_sel:[0,0,1,0]
	v_cvt_scalef32_pk_fp4_f32 v24, v40, v41, 1.0 op_sel:[0,0,1,0]
	v_cvt_scalef32_pk_fp4_f32 v25, v48, v49, 1.0 op_sel:[0,0,1,0]
	v_lshl_add_u64 v[26:27], s[92:93], 0, v[26:27]
	v_lshlrev_b64 v[28:29], 10, v[8:9]
	v_cvt_scalef32_pk_fp4_f32 v23, v34, v35, 1.0 op_sel:[0,0,0,1]
	v_cvt_scalef32_pk_fp4_f32 v24, v42, v43, 1.0 op_sel:[0,0,0,1]
	v_cvt_scalef32_pk_fp4_f32 v25, v50, v51, 1.0 op_sel:[0,0,0,1]
	v_lshl_add_u64 v[26:27], v[26:27], 0, v[28:29]
	v_cvt_scalef32_pk_fp4_f32 v23, v36, v37, 1.0 op_sel:[0,0,1,1]
	v_cvt_scalef32_pk_fp4_f32 v24, v44, v45, 1.0 op_sel:[0,0,1,1]
	v_cvt_scalef32_pk_fp4_f32 v25, v52, v53, 1.0 op_sel:[0,0,1,1]
	v_lshl_add_u64 v[26:27], v[26:27], 0, v[6:7]
	global_store_dwordx4 v[26:27], v[22:25], off
	s_and_saveexec_b64 s[4:5], s[0:1]
	s_cbranch_execz .LBB0_1906
	v_cndmask_b32_e64 v22, v19, v20, s[2:3]
	v_mov_b32_e32 v23, v3
	v_lshl_add_u64 v[22:23], s[92:93], 0, v[22:23]
	v_lshl_add_u64 v[8:9], v[8:9], 2, v[22:23]
	global_store_dword v[8:9], v21, off
	s_branch .LBB0_1906
